# v89 + xgenstore: XCD leader releases local workgroups with a plain store of the arrival count into an XCD-local word (L2-resident), pollers read that word
# speedup vs baseline: 1.0171x; 1.0007x over previous
.LBB0_748:
	s_or_b64 exec, exec, s[14:15]
	v_cvt_f32_u32_e32 v6, v4
	s_waitcnt vmcnt(0)
	v_readfirstlane_b32 s7, v5
	v_sub_u32_e32 v5, 0, v4
	v_rcp_iflag_f32_e32 v6, v6
	v_add_u32_e32 v7, s7, v3
	v_mul_f32_e32 v6, 0x4f7ffffe, v6
	v_cvt_u32_f32_e32 v6, v6
	v_mul_lo_u32 v3, v5, v6
	v_mul_hi_u32 v3, v6, v3
	v_add_u32_e32 v3, v6, v3
	v_mul_hi_u32 v3, v7, v3
	v_mul_lo_u32 v5, v3, v4
	v_sub_u32_e32 v5, v7, v5
	v_add_u32_e32 v6, 1, v3
	v_cmp_ge_u32_e32 vcc, v5, v4
	s_nop 1
	v_cndmask_b32_e32 v3, v3, v6, vcc
	v_sub_u32_e32 v6, v5, v4
	v_cndmask_b32_e32 v5, v5, v6, vcc
	v_add_u32_e32 v6, 1, v3
	v_cmp_ge_u32_e32 vcc, v5, v4
	v_add_u32_e32 v5, 1, v7
	s_nop 0
	v_cndmask_b32_e32 v3, v3, v6, vcc
	v_mul_lo_u32 v6, v4, v3
	v_add_u32_e32 v4, v6, v4
	v_cmp_ne_u32_e32 vcc, v5, v4
	s_and_saveexec_b64 s[8:9], vcc
	s_xor_b64 s[14:15], exec, s[8:9]
	s_cbranch_execz .LBB0_762
	buffer_inv sc1
	v_readlane_b32 s8, v255, 6
	v_readlane_b32 s9, v255, 7
	s_waitcnt lgkmcnt(0)
	s_nop 3
	global_load_dword v2, v181, s[8:9] offset:2048 sc1
	s_waitcnt vmcnt(0)
	v_cmp_lt_u32_e32 vcc, v2, v4
	s_and_saveexec_b64 s[18:19], vcc
	s_cbranch_execz .LBB0_761
	s_mov_b32 s7, 1
	s_mov_b64 s[22:23], 0
	s_branch .LBB0_752

.LBB0_754:
	v_readlane_b32 s8, v255, 6
	v_readlane_b32 s9, v255, 7
	s_add_i32 s7, s7, 1
	s_mov_b64 s[28:29], -1
	s_nop 2
	global_load_dword v2, v181, s[8:9] offset:2048 sc1
	s_waitcnt vmcnt(0)
	v_cmp_ge_u32_e32 vcc, v2, v4
	s_orn2_b64 s[26:27], vcc, exec
	s_branch .LBB0_751

.LBB0_779:
	s_or_b64 exec, exec, s[14:15]
	s_mov_b64 s[14:15], exec
	v_mbcnt_lo_u32_b32 v2, s14, 0
	v_mbcnt_hi_u32_b32 v2, s15, v2
	v_cmp_eq_u32_e32 vcc, 0, v2
	s_and_saveexec_b64 s[18:19], vcc
	s_cbranch_execz .LBB0_781
	s_bcnt1_i32_b64 s7, s[14:15]
	v_readlane_b32 s8, v255, 6
	v_mov_b32_e32 v2, s7
	v_readlane_b32 s9, v255, 7
	s_nop 4
	v_add_u32_e32 v3, 1, v7
	global_store_dword v181, v3, s[8:9] offset:2048
	global_atomic_add v181, v2, s[8:9]

.LBB0_963:
	s_or_b64 exec, exec, s[14:15]
	v_cvt_f32_u32_e32 v6, v4
	s_waitcnt vmcnt(0)
	v_readfirstlane_b32 s6, v5
	v_sub_u32_e32 v5, 0, v4
	v_rcp_iflag_f32_e32 v6, v6
	v_add_u32_e32 v7, s6, v3
	v_mul_f32_e32 v6, 0x4f7ffffe, v6
	v_cvt_u32_f32_e32 v6, v6
	v_mul_lo_u32 v3, v5, v6
	v_mul_hi_u32 v3, v6, v3
	v_add_u32_e32 v3, v6, v3
	v_mul_hi_u32 v3, v7, v3
	v_mul_lo_u32 v5, v3, v4
	v_sub_u32_e32 v5, v7, v5
	v_add_u32_e32 v6, 1, v3
	v_cmp_ge_u32_e32 vcc, v5, v4
	s_nop 1
	v_cndmask_b32_e32 v3, v3, v6, vcc
	v_sub_u32_e32 v6, v5, v4
	v_cndmask_b32_e32 v5, v5, v6, vcc
	v_add_u32_e32 v6, 1, v3
	v_cmp_ge_u32_e32 vcc, v5, v4
	v_add_u32_e32 v5, 1, v7
	s_nop 0
	v_cndmask_b32_e32 v3, v3, v6, vcc
	v_mul_lo_u32 v6, v4, v3
	v_add_u32_e32 v4, v6, v4
	v_cmp_ne_u32_e32 vcc, v5, v4
	s_and_saveexec_b64 s[6:7], vcc
	s_xor_b64 s[14:15], exec, s[6:7]
	s_cbranch_execz .LBB0_977
	buffer_inv sc1
	v_readlane_b32 s6, v255, 6
	v_readlane_b32 s7, v255, 7
	s_waitcnt lgkmcnt(0)
	s_nop 3
	global_load_dword v2, v181, s[6:7] offset:2048 sc1
	s_waitcnt vmcnt(0)
	v_cmp_lt_u32_e32 vcc, v2, v4
	s_and_saveexec_b64 s[18:19], vcc
	s_cbranch_execz .LBB0_976
	s_mov_b32 s6, 1
	s_mov_b64 s[22:23], 0
	s_branch .LBB0_967

.LBB0_969:
	v_readlane_b32 s8, v255, 6
	v_readlane_b32 s9, v255, 7
	s_add_i32 s6, s6, 1
	s_mov_b64 s[28:29], -1
	s_nop 2
	global_load_dword v2, v181, s[8:9] offset:2048 sc1
	s_waitcnt vmcnt(0)
	v_cmp_ge_u32_e32 vcc, v2, v4
	s_orn2_b64 s[26:27], vcc, exec
	s_branch .LBB0_966

.LBB0_994:
	s_or_b64 exec, exec, s[14:15]
	s_mov_b64 s[14:15], exec
	v_mbcnt_lo_u32_b32 v2, s14, 0
	v_mbcnt_hi_u32_b32 v2, s15, v2
	v_cmp_eq_u32_e32 vcc, 0, v2
	s_and_saveexec_b64 s[18:19], vcc
	s_cbranch_execz .LBB0_996
	s_bcnt1_i32_b64 s6, s[14:15]
	v_mov_b32_e32 v2, s6
	v_readlane_b32 s6, v255, 6
	v_readlane_b32 s7, v255, 7
	s_nop 4
	v_add_u32_e32 v3, 1, v7
	global_store_dword v181, v3, s[6:7] offset:2048
	global_atomic_add v181, v2, s[6:7]

.LBB0_1372:
	s_or_b64 exec, exec, s[18:19]
	v_cvt_f32_u32_e32 v6, v4
	s_waitcnt vmcnt(0)
	v_readfirstlane_b32 s7, v5
	v_sub_u32_e32 v5, 0, v4
	v_rcp_iflag_f32_e32 v6, v6
	v_add_u32_e32 v7, s7, v3
	v_mul_f32_e32 v6, 0x4f7ffffe, v6
	v_cvt_u32_f32_e32 v6, v6
	v_mul_lo_u32 v3, v5, v6
	v_mul_hi_u32 v3, v6, v3
	v_add_u32_e32 v3, v6, v3
	v_mul_hi_u32 v3, v7, v3
	v_mul_lo_u32 v5, v3, v4
	v_sub_u32_e32 v5, v7, v5
	v_add_u32_e32 v6, 1, v3
	v_cmp_ge_u32_e32 vcc, v5, v4
	s_nop 1
	v_cndmask_b32_e32 v3, v3, v6, vcc
	v_sub_u32_e32 v6, v5, v4
	v_cndmask_b32_e32 v5, v5, v6, vcc
	v_add_u32_e32 v6, 1, v3
	v_cmp_ge_u32_e32 vcc, v5, v4
	v_add_u32_e32 v5, 1, v7
	s_nop 0
	v_cndmask_b32_e32 v3, v3, v6, vcc
	v_mul_lo_u32 v6, v4, v3
	v_add_u32_e32 v4, v6, v4
	v_cmp_ne_u32_e32 vcc, v5, v4
	s_and_saveexec_b64 s[8:9], vcc
	s_xor_b64 s[18:19], exec, s[8:9]
	s_cbranch_execz .LBB0_1386
	buffer_inv sc1
	v_readlane_b32 s8, v255, 6
	v_readlane_b32 s9, v255, 7
	s_waitcnt lgkmcnt(0)
	s_nop 3
	global_load_dword v2, v181, s[8:9] offset:2048 sc1
	s_waitcnt vmcnt(0)
	v_cmp_lt_u32_e32 vcc, v2, v4
	s_and_saveexec_b64 s[22:23], vcc
	s_cbranch_execz .LBB0_1385
	s_mov_b32 s7, 1
	s_mov_b64 s[24:25], 0
	s_branch .LBB0_1376

.LBB0_1378:
	v_readlane_b32 s8, v255, 6
	v_readlane_b32 s9, v255, 7
	s_add_i32 s7, s7, 1
	s_mov_b64 s[30:31], -1
	s_nop 2
	global_load_dword v2, v181, s[8:9] offset:2048 sc1
	s_waitcnt vmcnt(0)
	v_cmp_ge_u32_e32 vcc, v2, v4
	s_orn2_b64 s[28:29], vcc, exec
	s_branch .LBB0_1375

.LBB0_1403:
	s_or_b64 exec, exec, s[18:19]
	s_mov_b64 s[18:19], exec
	v_mbcnt_lo_u32_b32 v2, s18, 0
	v_mbcnt_hi_u32_b32 v2, s19, v2
	v_cmp_eq_u32_e32 vcc, 0, v2
	s_and_saveexec_b64 s[22:23], vcc
	s_cbranch_execz .LBB0_1405
	s_bcnt1_i32_b64 s7, s[18:19]
	v_readlane_b32 s8, v255, 6
	v_mov_b32_e32 v2, s7
	v_readlane_b32 s9, v255, 7
	s_nop 4
	v_add_u32_e32 v3, 1, v7
	global_store_dword v181, v3, s[8:9] offset:2048
	global_atomic_add v181, v2, s[8:9]

.LBB0_1517:
	s_or_b64 exec, exec, s[10:11]
	v_cvt_f32_u32_e32 v6, v4
	s_waitcnt vmcnt(0)
	v_readfirstlane_b32 s6, v5
	v_sub_u32_e32 v5, 0, v4
	v_rcp_iflag_f32_e32 v6, v6
	v_add_u32_e32 v7, s6, v3
	v_mul_f32_e32 v6, 0x4f7ffffe, v6
	v_cvt_u32_f32_e32 v6, v6
	v_mul_lo_u32 v3, v5, v6
	v_mul_hi_u32 v3, v6, v3
	v_add_u32_e32 v3, v6, v3
	v_mul_hi_u32 v3, v7, v3
	v_mul_lo_u32 v5, v3, v4
	v_sub_u32_e32 v5, v7, v5
	v_add_u32_e32 v6, 1, v3
	v_cmp_ge_u32_e32 vcc, v5, v4
	s_nop 1
	v_cndmask_b32_e32 v3, v3, v6, vcc
	v_sub_u32_e32 v6, v5, v4
	v_cndmask_b32_e32 v5, v5, v6, vcc
	v_add_u32_e32 v6, 1, v3
	v_cmp_ge_u32_e32 vcc, v5, v4
	v_add_u32_e32 v5, 1, v7
	s_nop 0
	v_cndmask_b32_e32 v3, v3, v6, vcc
	v_mul_lo_u32 v6, v4, v3
	v_add_u32_e32 v4, v6, v4
	v_cmp_ne_u32_e32 vcc, v5, v4
	s_and_saveexec_b64 s[6:7], vcc
	s_xor_b64 s[10:11], exec, s[6:7]
	s_cbranch_execz .LBB0_1531
	buffer_inv sc1
	v_readlane_b32 s6, v255, 6
	v_readlane_b32 s7, v255, 7
	s_waitcnt lgkmcnt(0)
	s_nop 3
	global_load_dword v2, v181, s[6:7] offset:2048 sc1
	s_waitcnt vmcnt(0)
	v_cmp_lt_u32_e32 vcc, v2, v4
	s_and_saveexec_b64 s[14:15], vcc
	s_cbranch_execz .LBB0_1530
	s_mov_b32 s6, 1
	s_mov_b64 s[18:19], 0
	s_branch .LBB0_1521

.LBB0_1523:
	v_readlane_b32 s8, v255, 6
	v_readlane_b32 s9, v255, 7
	s_add_i32 s6, s6, 1
	s_mov_b64 s[26:27], -1
	s_nop 2
	global_load_dword v2, v181, s[8:9] offset:2048 sc1
	s_waitcnt vmcnt(0)
	v_cmp_ge_u32_e32 vcc, v2, v4
	s_orn2_b64 s[24:25], vcc, exec
	s_branch .LBB0_1520

.LBB0_1548:
	s_or_b64 exec, exec, s[10:11]
	s_mov_b64 s[10:11], exec
	v_mbcnt_lo_u32_b32 v2, s10, 0
	v_mbcnt_hi_u32_b32 v2, s11, v2
	v_cmp_eq_u32_e32 vcc, 0, v2
	s_and_saveexec_b64 s[14:15], vcc
	s_cbranch_execz .LBB0_1550
	s_bcnt1_i32_b64 s6, s[10:11]
	v_mov_b32_e32 v2, s6
	v_readlane_b32 s6, v255, 6
	v_readlane_b32 s7, v255, 7
	s_nop 4
	v_add_u32_e32 v3, 1, v7
	global_store_dword v181, v3, s[6:7] offset:2048
	global_atomic_add v181, v2, s[6:7]
